# fast path v4: + staging ds_writes of the prefetched K/V tiles interleaved into the tile-B PV MFMA shadow
# speedup vs baseline: 1.0126x; 1.0108x over previous
; DI void attn_item(const Params& p, int g, int seq, int hd, int qt, int m, char* smem, int split_j, int sub) {
;     ...
;   auto compute = [&](int st, int buf) __attribute__((always_inline)) {
;     const int k0 = (tbase + st) * 32, h = h_, l31 = l31_;
;     const bf16_t* Kb = Ks + buf * 32 * 72; const bf16_t* Vb = Vs + buf * 128 * 40;
;     const int rmin = k0 - (qw0 + 31), rmax = k0 + 31 - qw0;
;     const bool farL = rmax <= -128, farR = rmin >= 128;
;     if (!farL && region == 0) { rescale(__builtin_amdgcn_exp2f(cneg)); region = 1; }
;     if (farR && region == 1) { rescale(__builtin_amdgcn_exp2f(-cpos)); region = 2; }
;     bf16x8 kf[4], vf[2][4];
; #pragma unroll
;     for (int s = 0; s < 4; ++s) kf[s] = *(const bf16x8*)(Kb + l31 * 72 + s * 16 + h * 8);
; #pragma unroll
;     for (int s2 = 0; s2 < 2; ++s2)
; #pragma unroll
;       for (int dt = 0; dt < 4; ++dt) vf[s2][dt] = *(const bf16x8*)(Vb + (dt * 32 + l31) * 40 + s2 * 16 + h * 8);
;     __builtin_amdgcn_sched_barrier(0);
;     f32x16 X;
; #pragma unroll
;     for (int r = 0; r < 16; ++r) X[r] = 0.f;
; #pragma unroll
;     for (int s = 0; s < 4; ++s) X = MFMA32(kf[s], qf[s], X);
;     if (farL || farR) {
; #pragma unroll
;       for (int r = 0; r < 16; ++r) X[r] = __builtin_amdgcn_exp2f(X[r]);
;     } else {
;       const int rel0 = k0 - (qw0 + l31) + 128;
; #pragma unroll
;       for (int r = 0; r < 16; ++r) { int idx = rel0 + crow(r, h); idx = idx < 0 ? 0 : (idx > 256 ? 256 : idx); X[r] = __builtin_amdgcn_exp2f(X[r] + tab[idx]); }
;     }
;     bf16x8 pf[2];
; #pragma unroll
;     for (int s2 = 0; s2 < 2; ++s2) {
;       u32x4 w; w.x = pk_bf16(X[8 * s2], X[8 * s2 + 1]); w.y = pk_bf16(X[8 * s2 + 2], X[8 * s2 + 3]); w.z = pk_bf16(X[8 * s2 + 4], X[8 * s2 + 5]); w.w = pk_bf16(X[8 * s2 + 6], X[8 * s2 + 7]);
;       ls2 += (f32x2){X[8 * s2], X[8 * s2 + 1]}; ls2 += (f32x2){X[8 * s2 + 2], X[8 * s2 + 3]};
;       ls2 += (f32x2){X[8 * s2 + 4], X[8 * s2 + 5]}; ls2 += (f32x2){X[8 * s2 + 6], X[8 * s2 + 7]};
;       pf[s2] = __builtin_bit_cast(bf16x8, w);
;     }
; #pragma unroll
;     for (int s2 = 0; s2 < 2; ++s2)
; #pragma unroll
;       for (int dt = 0; dt < 4; ++dt) O[dt] = MFMA32(pf[s2], vf[s2][dt], O[dt]);
;   };
;   load_tile(0, rkA, rvA0, rvA1);
;   load_tile(1, rkB, rvB0, rvB1);
;   __syncthreads();
;   store_tile(0, rkA, rvA0, rvA1);
;   store_tile(1, rkB, rvB0, rvB1);
;   __syncthreads();
.Lat2_fast:
	s_add_i32 s10, s6, -3
	s_and_b32 s16, s10, 2
	s_mul_i32 s10, s16, 0x1200
	s_mul_i32 s18, s16, 0x2800
	v_add_u32_e32 v192, s10, v191
	v_add_u32_e32 v244, s18, v196
	ds_read_b128 v[64:67], v192
	ds_read_b128 v[80:83], v192 offset:32
	ds_read_b128 v[84:87], v192 offset:64
	ds_read_b128 v[88:91], v192 offset:96
	ds_read_b128 v[220:223], v192 offset:4608
	ds_read_b128 v[224:227], v192 offset:4640
	ds_read_b128 v[236:239], v192 offset:4672
	ds_read_b128 v[240:243], v192 offset:4704
	ds_read_b128 v[156:159], v244 offset:18432
	ds_read_b128 v[160:163], v244 offset:20992
	ds_read_b128 v[164:167], v244 offset:23552
	ds_read_b128 v[152:155], v244 offset:26112
	s_waitcnt lgkmcnt(11)
	v_mfma_f32_32x32x16_bf16 v[64:79], v[64:67], v[104:107], 0
	s_waitcnt lgkmcnt(10)
	v_mfma_f32_32x32x16_bf16 v[64:79], v[80:83], v[108:111], v[64:79]
	s_waitcnt lgkmcnt(9)
	v_mfma_f32_32x32x16_bf16 v[64:79], v[84:87], v[112:115], v[64:79]
	s_waitcnt lgkmcnt(8)
	v_mfma_f32_32x32x16_bf16 v[64:79], v[88:91], v[116:119], v[64:79]
	ds_read_b128 v[148:151], v244 offset:18464
	ds_read_b128 v[144:147], v244 offset:21024
	ds_read_b128 v[136:139], v244 offset:23584
	ds_read_b128 v[140:143], v244 offset:26144
	s_waitcnt lgkmcnt(11)
	v_mfma_f32_32x32x16_bf16 v[80:95], v[220:223], v[104:107], 0
	s_waitcnt lgkmcnt(10)
	v_mfma_f32_32x32x16_bf16 v[80:95], v[224:227], v[108:111], v[80:95]
	v_exp_f32_e32 v64, v64
	v_exp_f32_e32 v65, v65
	v_exp_f32_e32 v66, v66
	v_exp_f32_e32 v67, v67
	v_exp_f32_e32 v68, v68
	v_exp_f32_e32 v69, v69
	s_waitcnt lgkmcnt(9)
	v_mfma_f32_32x32x16_bf16 v[80:95], v[236:239], v[112:115], v[80:95]
	v_exp_f32_e32 v70, v70
	v_exp_f32_e32 v71, v71
	v_exp_f32_e32 v72, v72
	v_exp_f32_e32 v73, v73
	v_exp_f32_e32 v74, v74
	v_exp_f32_e32 v75, v75
	s_waitcnt lgkmcnt(8)
	v_mfma_f32_32x32x16_bf16 v[80:95], v[240:243], v[116:119], v[80:95]
	v_exp_f32_e32 v76, v76
	v_exp_f32_e32 v77, v77
	v_exp_f32_e32 v78, v78
	v_exp_f32_e32 v79, v79
	v_pk_add_f32 v[246:247], v[66:67], v[70:71]
	v_pk_add_f32 v[186:187], v[186:187], v[64:65]
	v_pk_add_f32 v[246:247], v[246:247], v[74:75]
	v_pk_add_f32 v[186:187], v[186:187], v[68:69]
	v_pk_add_f32 v[246:247], v[246:247], v[78:79]
	v_pk_add_f32 v[186:187], v[186:187], v[72:73]
	v_pk_add_f32 v[186:187], v[186:187], v[76:77]
	v_pk_add_f32 v[186:187], v[186:187], v[246:247]
	v_cvt_pk_bf16_f32 v64, v64, v65
	v_cvt_pk_bf16_f32 v65, v66, v67
	v_cvt_pk_bf16_f32 v66, v68, v69
	v_cvt_pk_bf16_f32 v67, v70, v71
	v_cvt_pk_bf16_f32 v68, v72, v73
	v_cvt_pk_bf16_f32 v69, v74, v75
	v_cvt_pk_bf16_f32 v70, v76, v77
	v_cvt_pk_bf16_f32 v71, v78, v79
	s_waitcnt lgkmcnt(7)
	v_mfma_f32_32x32x16_bf16 v[48:63], v[64:67], v[156:159], v[48:63]
	ds_read_b128 v[156:159], v244 offset:28672
	v_exp_f32_e32 v80, v80
	v_exp_f32_e32 v81, v81
	v_exp_f32_e32 v82, v82
	s_waitcnt lgkmcnt(7)
	v_mfma_f32_32x32x16_bf16 v[32:47], v[64:67], v[160:163], v[32:47]
	ds_read_b128 v[160:163], v244 offset:31232
	v_exp_f32_e32 v83, v83
	v_exp_f32_e32 v84, v84
	v_exp_f32_e32 v85, v85
	s_waitcnt lgkmcnt(7)
	v_mfma_f32_32x32x16_bf16 v[16:31], v[64:67], v[164:167], v[16:31]
	ds_read_b128 v[164:167], v244 offset:33792
	v_exp_f32_e32 v86, v86
	v_exp_f32_e32 v87, v87
	v_exp_f32_e32 v88, v88
	s_waitcnt lgkmcnt(7)
	v_mfma_f32_32x32x16_bf16 v[0:15], v[64:67], v[152:155], v[0:15]
	ds_read_b128 v[152:155], v244 offset:36352
	v_exp_f32_e32 v89, v89
	v_exp_f32_e32 v90, v90
	v_exp_f32_e32 v91, v91
	s_waitcnt lgkmcnt(7)
	v_mfma_f32_32x32x16_bf16 v[48:63], v[68:71], v[148:151], v[48:63]
	ds_read_b128 v[148:151], v244 offset:28704
	v_exp_f32_e32 v92, v92
	v_exp_f32_e32 v93, v93
	v_exp_f32_e32 v94, v94
	v_exp_f32_e32 v95, v95
	s_waitcnt lgkmcnt(7)
	v_mfma_f32_32x32x16_bf16 v[32:47], v[68:71], v[144:147], v[32:47]
	ds_read_b128 v[144:147], v244 offset:31264
	v_pk_add_f32 v[246:247], v[82:83], v[86:87]
	v_pk_add_f32 v[186:187], v[186:187], v[80:81]
	v_pk_add_f32 v[246:247], v[246:247], v[90:91]
	v_pk_add_f32 v[186:187], v[186:187], v[84:85]
	s_waitcnt lgkmcnt(7)
	v_mfma_f32_32x32x16_bf16 v[16:31], v[68:71], v[136:139], v[16:31]
	ds_read_b128 v[136:139], v244 offset:33824
	v_pk_add_f32 v[246:247], v[246:247], v[94:95]
	v_pk_add_f32 v[186:187], v[186:187], v[88:89]
	v_pk_add_f32 v[186:187], v[186:187], v[92:93]
	v_pk_add_f32 v[186:187], v[186:187], v[246:247]
	s_waitcnt lgkmcnt(7)
	v_mfma_f32_32x32x16_bf16 v[0:15], v[68:71], v[140:143], v[0:15]
	ds_read_b128 v[140:143], v244 offset:36384
	v_cvt_pk_bf16_f32 v80, v80, v81
	v_cvt_pk_bf16_f32 v81, v82, v83
	v_cvt_pk_bf16_f32 v82, v84, v85
	v_cvt_pk_bf16_f32 v83, v86, v87
	v_cvt_pk_bf16_f32 v84, v88, v89
	v_cvt_pk_bf16_f32 v85, v90, v91
	v_cvt_pk_bf16_f32 v86, v92, v93
	v_cvt_pk_bf16_f32 v87, v94, v95
	s_andn2_b64 vcc, exec, s[8:9]
	s_cbranch_vccnz .Lat2_pvplain
	s_xor_b32 s7, s16, 2
	s_mul_i32 s8, s7, 0x2800
	s_add_i32 s8, s8, 32
	s_mulk_i32 s7, 0x1200
	v_add_u32_e32 v192, s7, v169
	v_add3_u32 v244, s8, v189, v190
	s_addk_i32 s8, 0x2800
	s_waitcnt lgkmcnt(7)
	v_mfma_f32_32x32x16_bf16 v[48:63], v[80:83], v[156:159], v[48:63]
	s_waitcnt vmcnt(5)
	ds_write_b128 v192, v[96:99]
	s_waitcnt lgkmcnt(7)
	v_mfma_f32_32x32x16_bf16 v[32:47], v[80:83], v[160:163], v[32:47]
	s_waitcnt vmcnt(4)
	ds_write_b128 v244, v[100:103] offset:18432
	s_waitcnt lgkmcnt(7)
	v_mfma_f32_32x32x16_bf16 v[16:31], v[80:83], v[164:167], v[16:31]
	s_waitcnt vmcnt(3)
	ds_write_b128 v244, v[120:123] offset:23552
	s_waitcnt lgkmcnt(7)
	v_mfma_f32_32x32x16_bf16 v[0:15], v[80:83], v[152:155], v[0:15]
	s_waitcnt vmcnt(2)
	ds_write_b128 v192, v[124:127] offset:4608
	s_waitcnt lgkmcnt(7)
	v_mfma_f32_32x32x16_bf16 v[48:63], v[84:87], v[148:151], v[48:63]
	v_add3_u32 v192, s8, v189, v190
	s_waitcnt vmcnt(1)
	ds_write_b128 v192, v[128:131] offset:18432
	s_waitcnt lgkmcnt(7)
	v_mfma_f32_32x32x16_bf16 v[32:47], v[84:87], v[144:147], v[32:47]
	s_waitcnt vmcnt(0)
	ds_write_b128 v192, v[132:135] offset:23552
	s_waitcnt lgkmcnt(7)
	v_mfma_f32_32x32x16_bf16 v[16:31], v[84:87], v[136:139], v[16:31]
	s_waitcnt lgkmcnt(6)
	v_mfma_f32_32x32x16_bf16 v[0:15], v[84:87], v[140:143], v[0:15]
	s_branch .Lat2_bot
.Lat2_pvplain:
	s_waitcnt lgkmcnt(7)
	v_mfma_f32_32x32x16_bf16 v[48:63], v[80:83], v[156:159], v[48:63]
	s_waitcnt lgkmcnt(6)
	v_mfma_f32_32x32x16_bf16 v[32:47], v[80:83], v[160:163], v[32:47]
	s_waitcnt lgkmcnt(5)
	v_mfma_f32_32x32x16_bf16 v[16:31], v[80:83], v[164:167], v[16:31]
	s_waitcnt lgkmcnt(4)
	v_mfma_f32_32x32x16_bf16 v[0:15], v[80:83], v[152:155], v[0:15]
	s_waitcnt lgkmcnt(3)
	v_mfma_f32_32x32x16_bf16 v[48:63], v[84:87], v[148:151], v[48:63]
	s_waitcnt lgkmcnt(2)
	v_mfma_f32_32x32x16_bf16 v[32:47], v[84:87], v[144:147], v[32:47]
	s_waitcnt lgkmcnt(1)
	v_mfma_f32_32x32x16_bf16 v[16:31], v[84:87], v[136:139], v[16:31]
	s_waitcnt lgkmcnt(0)
	v_mfma_f32_32x32x16_bf16 v[0:15], v[84:87], v[140:143], v[0:15]
